# EpiM1/EpiM2 (branch-projection gated merge GEMMs) epilogues de-laddered: gate and running-sum loads hoisted (M1: all 16 up front; M2: 32 loads issued 3 row-blocks ahead) with exact counted waits; EpiK
# speedup vs baseline: 1.0253x; 1.0026x over previous
; __device__ __forceinline__ void st_bf8(bf16* p, f32x4 a, f32x4 b) { u32x4 w; w.x = pk2(a[0], a[1]); w.y = pk2(a[2], a[3]); w.z = pk2(b[0], b[1]); w.w = pk2(b[2], b[3]); *(u32x4*)p = w; }
; __device__ __forceinline__ void ld_bf8(const bf16* p, f32x4& a, f32x4& b) { const u32x4 w = *(const u32x4*)p; a = (f32x4){bflo(w.x), bfhi(w.x), bflo(w.y), bfhi(w.y)}; b = (f32x4){bflo(w.z), bfhi(w.z), bflo(w.w), bfhi(w.w)}; }
;     __device__ __forceinline__ void operator()(AccRef acc, const pg8::Unit& u, int wr, int wc, int fr, int fq) const {
;         const int c0 = u.pn * 256;
;         EPI_LOOP_P( f32x4 g0, g1; ld_bf8(Gt + rw * 1024 + c0 + cl, g0, g1); st_bf8(MG + rw * 1024 + c0 + cl, g0 * v0, g1 * v1); )
;     }
.LBB0_463:
	v_lshl_add_u32 v140, s47, 8, v142
	s_lshl_b32 s20, s48, 8
	v_ashrrev_i32_e32 v141, 31, v140
	s_ashr_i32 s21, s20, 31
	v_lshlrev_b64 v[150:151], 11, v[140:141]
	v_lshl_add_u64 v[146:147], s[12:13], 0, v[150:151]
	s_lshl_b64 s[20:21], s[20:21], 1
	v_lshl_add_u64 v[146:147], v[146:147], 0, s[20:21]
	v_lshl_add_u64 v[152:153], v[146:147], 0, v[184:185]
	v_lshlrev_b32_e32 v244, 11, v140
	v_add3_u32 v244, v244, s20, v184
	global_load_dwordx4 v[158:161], v244, s[12:13]
	global_load_dwordx4 v[162:165], v244, s[12:13] offset:256
	v_add_u32_e32 v244, 0x8000, v244
	global_load_dwordx4 v[166:169], v244, s[12:13]
	global_load_dwordx4 v[170:173], v244, s[12:13] offset:256
	v_add_u32_e32 v244, 0x8000, v244
	global_load_dwordx4 v[174:177], v244, s[12:13]
	global_load_dwordx4 v[178:181], v244, s[12:13] offset:256
	v_add_u32_e32 v244, 0x8000, v244
	global_load_dwordx4 v[190:193], v244, s[12:13]
	global_load_dwordx4 v[196:199], v244, s[12:13] offset:256
	v_add_u32_e32 v244, 0x28000, v244
	global_load_dwordx4 v[200:203], v244, s[12:13]
	global_load_dwordx4 v[212:215], v244, s[12:13] offset:256
	v_add_u32_e32 v244, 0x8000, v244
	global_load_dwordx4 v[216:219], v244, s[12:13]
	global_load_dwordx4 v[220:223], v244, s[12:13] offset:256
	v_add_u32_e32 v244, 0x8000, v244
	global_load_dwordx4 v[224:227], v244, s[12:13]
	global_load_dwordx4 v[228:231], v244, s[12:13] offset:256
	v_add_u32_e32 v244, 0x8000, v244
	global_load_dwordx4 v[232:235], v244, s[12:13]
	global_load_dwordx4 v[236:239], v244, s[12:13] offset:256
	v_lshl_add_u64 v[150:151], s[10:11], 0, v[150:151]
	v_lshl_add_u64 v[150:151], v[150:151], 0, s[20:21]
	v_lshl_add_u64 v[150:151], v[150:151], 0, v[184:185]
	s_and_b64 vcc, exec, s[0:1]
	s_mov_b64 s[0:1], -1
	s_waitcnt vmcnt(15)
	v_lshlrev_b32_e32 v154, 16, v158
	v_and_b32_e32 v155, 0xffff0000, v158
	v_lshlrev_b32_e32 v146, 16, v159
	v_and_b32_e32 v147, 0xffff0000, v159
	v_lshlrev_b32_e32 v156, 16, v160
	v_and_b32_e32 v157, 0xffff0000, v160
	v_lshlrev_b32_e32 v148, 16, v161
	v_and_b32_e32 v149, 0xffff0000, v161
	v_pk_mul_f32 v[126:127], v[126:127], v[146:147]
	v_pk_mul_f32 v[124:125], v[124:125], v[154:155]
	v_pk_mul_f32 v[146:147], v[122:123], v[148:149]
	v_pk_mul_f32 v[122:123], v[120:121], v[156:157]
	v_cvt_pk_bf16_f32 v120, v124, v125
	v_cvt_pk_bf16_f32 v121, v126, v127
	v_cvt_pk_bf16_f32 v122, v122, v123
	v_cvt_pk_bf16_f32 v123, v146, v147
	global_store_dwordx4 v[150:151], v[120:123], off
	s_nop 1
	v_or_b32_e32 v124, 16, v140
	v_ashrrev_i32_e32 v125, 31, v124
	v_lshlrev_b64 v[124:125], 11, v[124:125]
	v_lshl_add_u64 v[126:127], s[12:13], 0, v[124:125]
	v_lshl_add_u64 v[126:127], v[126:127], 0, s[20:21]
	v_lshl_add_u64 v[126:127], v[126:127], 0, v[184:185]
	s_waitcnt vmcnt(15)
	v_lshlrev_b32_e32 v146, 16, v162
	v_and_b32_e32 v147, 0xffff0000, v162
	v_lshlrev_b32_e32 v120, 16, v163
	v_and_b32_e32 v121, 0xffff0000, v163
	v_lshlrev_b32_e32 v148, 16, v164
	v_and_b32_e32 v149, 0xffff0000, v164
	v_lshlrev_b32_e32 v122, 16, v165
	v_and_b32_e32 v123, 0xffff0000, v165
	v_pk_mul_f32 v[118:119], v[118:119], v[120:121]
	v_pk_mul_f32 v[116:117], v[116:117], v[146:147]
	v_pk_mul_f32 v[120:121], v[114:115], v[122:123]
	v_pk_mul_f32 v[114:115], v[112:113], v[148:149]
	v_cvt_pk_bf16_f32 v112, v116, v117
	v_cvt_pk_bf16_f32 v113, v118, v119
	v_cvt_pk_bf16_f32 v114, v114, v115
	v_cvt_pk_bf16_f32 v115, v120, v121
	global_store_dwordx4 v[150:151], v[112:115], off offset:256
	s_nop 1
	v_lshl_add_u64 v[116:117], s[10:11], 0, v[124:125]
	v_lshl_add_u64 v[116:117], v[116:117], 0, s[20:21]
	v_lshl_add_u64 v[116:117], v[116:117], 0, v[184:185]
	s_waitcnt vmcnt(15)
	v_lshlrev_b32_e32 v118, 16, v166
	v_and_b32_e32 v119, 0xffff0000, v166
	v_lshlrev_b32_e32 v112, 16, v167
	v_and_b32_e32 v113, 0xffff0000, v167
	v_lshlrev_b32_e32 v120, 16, v168
	v_and_b32_e32 v121, 0xffff0000, v168
	v_lshlrev_b32_e32 v114, 16, v169
	v_and_b32_e32 v115, 0xffff0000, v169
	v_pk_mul_f32 v[110:111], v[110:111], v[112:113]
	v_pk_mul_f32 v[108:109], v[108:109], v[118:119]
	v_pk_mul_f32 v[112:113], v[106:107], v[114:115]
	v_pk_mul_f32 v[106:107], v[104:105], v[120:121]
	v_cvt_pk_bf16_f32 v104, v108, v109
	v_cvt_pk_bf16_f32 v105, v110, v111
	v_cvt_pk_bf16_f32 v106, v106, v107
	v_cvt_pk_bf16_f32 v107, v112, v113
	global_store_dwordx4 v[116:117], v[104:107], off
	s_nop 1
	v_or_b32_e32 v108, 32, v140
	v_ashrrev_i32_e32 v109, 31, v108
	v_lshlrev_b64 v[108:109], 11, v[108:109]
	v_lshl_add_u64 v[110:111], s[12:13], 0, v[108:109]
	v_lshl_add_u64 v[110:111], v[110:111], 0, s[20:21]
	v_lshl_add_u64 v[110:111], v[110:111], 0, v[184:185]
	s_waitcnt vmcnt(15)
	v_lshlrev_b32_e32 v112, 16, v170
	v_and_b32_e32 v113, 0xffff0000, v170
	v_lshlrev_b32_e32 v104, 16, v171
	v_and_b32_e32 v105, 0xffff0000, v171
	v_lshlrev_b32_e32 v114, 16, v172
	v_and_b32_e32 v115, 0xffff0000, v172
	v_lshlrev_b32_e32 v106, 16, v173
	v_and_b32_e32 v107, 0xffff0000, v173
	v_pk_mul_f32 v[102:103], v[102:103], v[104:105]
	v_pk_mul_f32 v[100:101], v[100:101], v[112:113]
	v_pk_mul_f32 v[104:105], v[98:99], v[106:107]
	v_pk_mul_f32 v[98:99], v[96:97], v[114:115]
	v_cvt_pk_bf16_f32 v96, v100, v101
	v_cvt_pk_bf16_f32 v97, v102, v103
	v_cvt_pk_bf16_f32 v98, v98, v99
	v_cvt_pk_bf16_f32 v99, v104, v105
	global_store_dwordx4 v[116:117], v[96:99], off offset:256
	s_nop 1
	v_lshl_add_u64 v[100:101], s[10:11], 0, v[108:109]
	v_lshl_add_u64 v[100:101], v[100:101], 0, s[20:21]
	v_lshl_add_u64 v[100:101], v[100:101], 0, v[184:185]
	s_waitcnt vmcnt(15)
; __device__ __forceinline__ void st_bf8(bf16* p, f32x4 a, f32x4 b) { u32x4 w; w.x = pk2(a[0], a[1]); w.y = pk2(a[2], a[3]); w.z = pk2(b[0], b[1]); w.w = pk2(b[2], b[3]); *(u32x4*)p = w; }
; __device__ __forceinline__ void ld_bf8(const bf16* p, f32x4& a, f32x4& b) { const u32x4 w = *(const u32x4*)p; a = (f32x4){bflo(w.x), bfhi(w.x), bflo(w.y), bfhi(w.y)}; b = (f32x4){bflo(w.z), bfhi(w.z), bflo(w.w), bfhi(w.w)}; }
;     __device__ __forceinline__ void operator()(AccRef acc, const pg8::Unit& u, int wr, int wc, int fr, int fq) const {
;         const int c0 = u.pn * 256;
;         EPI_LOOP_P( f32x4 g0, g1; ld_bf8(Gt + rw * 1024 + c0 + cl, g0, g1); st_bf8(MG + rw * 1024 + c0 + cl, g0 * v0, g1 * v1); )
	v_lshlrev_b32_e32 v102, 16, v174
	v_and_b32_e32 v103, 0xffff0000, v174
	v_lshlrev_b32_e32 v96, 16, v175
	v_and_b32_e32 v97, 0xffff0000, v175
	v_lshlrev_b32_e32 v104, 16, v176
	v_and_b32_e32 v105, 0xffff0000, v176
	v_lshlrev_b32_e32 v98, 16, v177
	v_and_b32_e32 v99, 0xffff0000, v177
	v_pk_mul_f32 v[94:95], v[94:95], v[96:97]
	v_pk_mul_f32 v[92:93], v[92:93], v[102:103]
	v_pk_mul_f32 v[96:97], v[90:91], v[98:99]
	v_pk_mul_f32 v[90:91], v[88:89], v[104:105]
	v_cvt_pk_bf16_f32 v88, v92, v93
	v_cvt_pk_bf16_f32 v89, v94, v95
	v_cvt_pk_bf16_f32 v90, v90, v91
	v_cvt_pk_bf16_f32 v91, v96, v97
	global_store_dwordx4 v[100:101], v[88:91], off
	s_nop 1
	v_or_b32_e32 v92, 48, v140
	v_ashrrev_i32_e32 v93, 31, v92
	v_lshlrev_b64 v[92:93], 11, v[92:93]
	v_lshl_add_u64 v[94:95], s[12:13], 0, v[92:93]
	v_lshl_add_u64 v[94:95], v[94:95], 0, s[20:21]
	v_lshl_add_u64 v[94:95], v[94:95], 0, v[184:185]
	s_waitcnt vmcnt(15)
	v_lshlrev_b32_e32 v96, 16, v178
	v_and_b32_e32 v97, 0xffff0000, v178
	v_lshlrev_b32_e32 v88, 16, v179
	v_and_b32_e32 v89, 0xffff0000, v179
	v_lshlrev_b32_e32 v98, 16, v180
	v_and_b32_e32 v99, 0xffff0000, v180
	v_lshlrev_b32_e32 v90, 16, v181
	v_and_b32_e32 v91, 0xffff0000, v181
	v_pk_mul_f32 v[86:87], v[86:87], v[88:89]
	v_pk_mul_f32 v[84:85], v[84:85], v[96:97]
	v_pk_mul_f32 v[88:89], v[82:83], v[90:91]
	v_pk_mul_f32 v[82:83], v[80:81], v[98:99]
	v_cvt_pk_bf16_f32 v80, v84, v85
	v_cvt_pk_bf16_f32 v81, v86, v87
	v_cvt_pk_bf16_f32 v82, v82, v83
	v_cvt_pk_bf16_f32 v83, v88, v89
	global_store_dwordx4 v[100:101], v[80:83], off offset:256
	s_nop 1
	v_lshl_add_u64 v[84:85], s[10:11], 0, v[92:93]
	v_lshl_add_u64 v[84:85], v[84:85], 0, s[20:21]
	v_lshl_add_u64 v[84:85], v[84:85], 0, v[184:185]
	s_waitcnt vmcnt(15)
	v_lshlrev_b32_e32 v86, 16, v190
	v_and_b32_e32 v87, 0xffff0000, v190
	v_lshlrev_b32_e32 v80, 16, v191
	v_and_b32_e32 v81, 0xffff0000, v191
	v_lshlrev_b32_e32 v88, 16, v192
	v_and_b32_e32 v89, 0xffff0000, v192
	v_lshlrev_b32_e32 v82, 16, v193
	v_and_b32_e32 v83, 0xffff0000, v193
	v_pk_mul_f32 v[78:79], v[78:79], v[80:81]
	v_pk_mul_f32 v[76:77], v[76:77], v[86:87]
	v_pk_mul_f32 v[80:81], v[74:75], v[82:83]
	v_pk_mul_f32 v[74:75], v[72:73], v[88:89]
	v_cvt_pk_bf16_f32 v72, v76, v77
	v_cvt_pk_bf16_f32 v73, v78, v79
	v_cvt_pk_bf16_f32 v74, v74, v75
	v_cvt_pk_bf16_f32 v75, v80, v81
	global_store_dwordx4 v[84:85], v[72:75], off
	s_nop 1
	v_add_u32_e32 v76, 0x80, v140
	v_ashrrev_i32_e32 v77, 31, v76
	v_lshlrev_b64 v[76:77], 11, v[76:77]
	v_lshl_add_u64 v[78:79], s[12:13], 0, v[76:77]
	v_lshl_add_u64 v[78:79], v[78:79], 0, s[20:21]
	v_lshl_add_u64 v[78:79], v[78:79], 0, v[184:185]
	s_waitcnt vmcnt(15)
	v_lshlrev_b32_e32 v80, 16, v196
	v_and_b32_e32 v81, 0xffff0000, v196
	v_lshlrev_b32_e32 v72, 16, v197
	v_and_b32_e32 v73, 0xffff0000, v197
	v_lshlrev_b32_e32 v82, 16, v198
	v_and_b32_e32 v83, 0xffff0000, v198
	v_lshlrev_b32_e32 v74, 16, v199
	v_and_b32_e32 v75, 0xffff0000, v199
	v_pk_mul_f32 v[70:71], v[70:71], v[72:73]
	v_pk_mul_f32 v[68:69], v[68:69], v[80:81]
	v_pk_mul_f32 v[72:73], v[66:67], v[74:75]
	v_pk_mul_f32 v[66:67], v[64:65], v[82:83]
	v_cvt_pk_bf16_f32 v64, v68, v69
	v_cvt_pk_bf16_f32 v65, v70, v71
	v_cvt_pk_bf16_f32 v66, v66, v67
	v_cvt_pk_bf16_f32 v67, v72, v73
	global_store_dwordx4 v[84:85], v[64:67], off offset:256
	s_nop 1
	v_lshl_add_u64 v[68:69], s[10:11], 0, v[76:77]
	v_lshl_add_u64 v[68:69], v[68:69], 0, s[20:21]
	v_lshl_add_u64 v[68:69], v[68:69], 0, v[184:185]
	s_waitcnt vmcnt(15)
	v_lshlrev_b32_e32 v70, 16, v200
	v_and_b32_e32 v71, 0xffff0000, v200
	v_lshlrev_b32_e32 v64, 16, v201
	v_and_b32_e32 v65, 0xffff0000, v201
	v_lshlrev_b32_e32 v72, 16, v202
	v_and_b32_e32 v73, 0xffff0000, v202
	v_lshlrev_b32_e32 v66, 16, v203
	v_and_b32_e32 v67, 0xffff0000, v203
	v_pk_mul_f32 v[62:63], v[62:63], v[64:65]
	v_pk_mul_f32 v[60:61], v[60:61], v[70:71]
	v_pk_mul_f32 v[64:65], v[58:59], v[66:67]
	v_pk_mul_f32 v[58:59], v[56:57], v[72:73]
	v_cvt_pk_bf16_f32 v56, v60, v61
	v_cvt_pk_bf16_f32 v57, v62, v63
	v_cvt_pk_bf16_f32 v58, v58, v59
	v_cvt_pk_bf16_f32 v59, v64, v65
	global_store_dwordx4 v[68:69], v[56:59], off
	s_nop 1
	v_add_u32_e32 v60, 0x90, v140
	v_ashrrev_i32_e32 v61, 31, v60
	v_lshlrev_b64 v[60:61], 11, v[60:61]
	v_lshl_add_u64 v[62:63], s[12:13], 0, v[60:61]
	v_lshl_add_u64 v[62:63], v[62:63], 0, s[20:21]
	v_lshl_add_u64 v[62:63], v[62:63], 0, v[184:185]
	s_waitcnt vmcnt(15)
	v_lshlrev_b32_e32 v64, 16, v212
	v_and_b32_e32 v65, 0xffff0000, v212
	v_lshlrev_b32_e32 v56, 16, v213
	v_and_b32_e32 v57, 0xffff0000, v213
	v_lshlrev_b32_e32 v66, 16, v214
	v_and_b32_e32 v67, 0xffff0000, v214
	v_lshlrev_b32_e32 v58, 16, v215
	v_and_b32_e32 v59, 0xffff0000, v215
	v_pk_mul_f32 v[54:55], v[54:55], v[56:57]
	v_pk_mul_f32 v[52:53], v[52:53], v[64:65]
	v_pk_mul_f32 v[56:57], v[50:51], v[58:59]
	v_pk_mul_f32 v[50:51], v[48:49], v[66:67]
	v_cvt_pk_bf16_f32 v48, v52, v53
	v_cvt_pk_bf16_f32 v49, v54, v55
	v_cvt_pk_bf16_f32 v50, v50, v51
	v_cvt_pk_bf16_f32 v51, v56, v57
	global_store_dwordx4 v[68:69], v[48:51], off offset:256
	s_nop 1
	v_lshl_add_u64 v[52:53], s[10:11], 0, v[60:61]
	v_lshl_add_u64 v[52:53], v[52:53], 0, s[20:21]
	v_lshl_add_u64 v[52:53], v[52:53], 0, v[184:185]
	s_waitcnt vmcnt(15)
; #define PG8_BAR __builtin_amdgcn_s_barrier()
; __device__ __forceinline__ void st_bf8(bf16* p, f32x4 a, f32x4 b) { u32x4 w; w.x = pk2(a[0], a[1]); w.y = pk2(a[2], a[3]); w.z = pk2(b[0], b[1]); w.w = pk2(b[2], b[3]); *(u32x4*)p = w; }
; __device__ __forceinline__ void ld_bf8(const bf16* p, f32x4& a, f32x4& b) { const u32x4 w = *(const u32x4*)p; a = (f32x4){bflo(w.x), bfhi(w.x), bflo(w.y), bfhi(w.y)}; b = (f32x4){bflo(w.z), bfhi(w.z), bflo(w.w), bfhi(w.w)}; }
; template <class Epi, class Sched, bool ALIGN_EPI = false, bool SP2 = false>
; __device__ __forceinline__ void gemm_phase(PG8_LAS unsigned char* lds, const Gemm g, const Sched& S, const Epi& E, const int tid_in) {
;     ...
;         if constexpr (ALIGN_EPI) { if (wr == 0) PG8_BAR; }
;         if constexpr (!Epi::AFTER_DRAIN) { E(acc, cur, wr, wc, fr, fq); S.done(cur); }
;         if (!has_next) break;
; #pragma unroll
;         for (int a = 0; a < 2; ++a)
; #pragma unroll
;             for (int b = 0; b < 2; ++b)
; #pragma unroll
;                 for (int m = 0; m < 4; ++m)
; #pragma unroll
;                     for (int n = 0; n < 2; ++n) acc[a][b][m][n] = (f32x4){0.f, 0.f, 0.f, 0.f};
;         cur = nxt; cA = nA; cB = nB; ++ui;
;         if constexpr (ALIGN_EPI) { if (wr == 1) PG8_BAR; }
;     __device__ __forceinline__ void operator()(AccRef acc, const pg8::Unit& u, int wr, int wc, int fr, int fq) const {
;         const int c0 = u.pn * 256;
;         EPI_LOOP_P( f32x4 g0, g1; ld_bf8(Gt + rw * 1024 + c0 + cl, g0, g1); st_bf8(MG + rw * 1024 + c0 + cl, g0 * v0, g1 * v1); )
	v_lshlrev_b32_e32 v54, 16, v216
	v_and_b32_e32 v55, 0xffff0000, v216
	v_lshlrev_b32_e32 v48, 16, v217
	v_and_b32_e32 v49, 0xffff0000, v217
	v_lshlrev_b32_e32 v56, 16, v218
	v_and_b32_e32 v57, 0xffff0000, v218
	v_lshlrev_b32_e32 v50, 16, v219
	v_and_b32_e32 v51, 0xffff0000, v219
	v_pk_mul_f32 v[46:47], v[46:47], v[48:49]
	v_pk_mul_f32 v[44:45], v[44:45], v[54:55]
	v_pk_mul_f32 v[48:49], v[42:43], v[50:51]
	v_pk_mul_f32 v[42:43], v[40:41], v[56:57]
	v_cvt_pk_bf16_f32 v40, v44, v45
	v_cvt_pk_bf16_f32 v41, v46, v47
	v_cvt_pk_bf16_f32 v42, v42, v43
	v_cvt_pk_bf16_f32 v43, v48, v49
	global_store_dwordx4 v[52:53], v[40:43], off
	s_nop 1
	v_add_u32_e32 v44, 0xa0, v140
	v_ashrrev_i32_e32 v45, 31, v44
	v_lshlrev_b64 v[44:45], 11, v[44:45]
	v_lshl_add_u64 v[46:47], s[12:13], 0, v[44:45]
	v_lshl_add_u64 v[46:47], v[46:47], 0, s[20:21]
	v_lshl_add_u64 v[46:47], v[46:47], 0, v[184:185]
	s_waitcnt vmcnt(15)
	v_lshlrev_b32_e32 v48, 16, v220
	v_and_b32_e32 v49, 0xffff0000, v220
	v_lshlrev_b32_e32 v40, 16, v221
	v_and_b32_e32 v41, 0xffff0000, v221
	v_lshlrev_b32_e32 v50, 16, v222
	v_and_b32_e32 v51, 0xffff0000, v222
	v_lshlrev_b32_e32 v42, 16, v223
	v_and_b32_e32 v43, 0xffff0000, v223
	v_pk_mul_f32 v[38:39], v[38:39], v[40:41]
	v_pk_mul_f32 v[36:37], v[36:37], v[48:49]
	v_pk_mul_f32 v[40:41], v[34:35], v[42:43]
	v_pk_mul_f32 v[34:35], v[32:33], v[50:51]
	v_cvt_pk_bf16_f32 v32, v36, v37
	v_cvt_pk_bf16_f32 v33, v38, v39
	v_cvt_pk_bf16_f32 v34, v34, v35
	v_cvt_pk_bf16_f32 v35, v40, v41
	global_store_dwordx4 v[52:53], v[32:35], off offset:256
	s_nop 1
	v_lshl_add_u64 v[36:37], s[10:11], 0, v[44:45]
	v_lshl_add_u64 v[36:37], v[36:37], 0, s[20:21]
	v_lshl_add_u64 v[36:37], v[36:37], 0, v[184:185]
	s_waitcnt vmcnt(15)
	v_lshlrev_b32_e32 v38, 16, v224
	v_and_b32_e32 v39, 0xffff0000, v224
	v_lshlrev_b32_e32 v32, 16, v225
	v_and_b32_e32 v33, 0xffff0000, v225
	v_lshlrev_b32_e32 v40, 16, v226
	v_and_b32_e32 v41, 0xffff0000, v226
	v_lshlrev_b32_e32 v34, 16, v227
	v_and_b32_e32 v35, 0xffff0000, v227
	v_pk_mul_f32 v[30:31], v[30:31], v[32:33]
	v_pk_mul_f32 v[28:29], v[28:29], v[38:39]
	v_pk_mul_f32 v[32:33], v[26:27], v[34:35]
	v_pk_mul_f32 v[26:27], v[24:25], v[40:41]
	v_cvt_pk_bf16_f32 v24, v28, v29
	v_cvt_pk_bf16_f32 v25, v30, v31
	v_cvt_pk_bf16_f32 v26, v26, v27
	v_cvt_pk_bf16_f32 v27, v32, v33
	global_store_dwordx4 v[36:37], v[24:27], off
	s_nop 1
	v_add_u32_e32 v28, 0xb0, v140
	v_ashrrev_i32_e32 v29, 31, v28
	v_lshlrev_b64 v[28:29], 11, v[28:29]
	v_lshl_add_u64 v[30:31], s[12:13], 0, v[28:29]
	v_lshl_add_u64 v[30:31], v[30:31], 0, s[20:21]
	v_lshl_add_u64 v[30:31], v[30:31], 0, v[184:185]
	s_waitcnt vmcnt(15)
	v_lshlrev_b32_e32 v32, 16, v228
	v_and_b32_e32 v33, 0xffff0000, v228
	v_lshlrev_b32_e32 v24, 16, v229
	v_and_b32_e32 v25, 0xffff0000, v229
	v_lshlrev_b32_e32 v34, 16, v230
	v_and_b32_e32 v35, 0xffff0000, v230
	v_lshlrev_b32_e32 v26, 16, v231
	v_and_b32_e32 v27, 0xffff0000, v231
	v_pk_mul_f32 v[22:23], v[22:23], v[24:25]
	v_pk_mul_f32 v[20:21], v[20:21], v[32:33]
	v_pk_mul_f32 v[24:25], v[18:19], v[26:27]
	v_pk_mul_f32 v[18:19], v[16:17], v[34:35]
	v_cvt_pk_bf16_f32 v16, v20, v21
	v_cvt_pk_bf16_f32 v17, v22, v23
	v_cvt_pk_bf16_f32 v18, v18, v19
	v_cvt_pk_bf16_f32 v19, v24, v25
	global_store_dwordx4 v[36:37], v[16:19], off offset:256
	s_nop 1
	v_lshl_add_u64 v[20:21], s[10:11], 0, v[28:29]
	v_lshl_add_u64 v[20:21], v[20:21], 0, s[20:21]
	v_lshl_add_u64 v[20:21], v[20:21], 0, v[184:185]
	s_waitcnt vmcnt(15)
	v_lshlrev_b32_e32 v22, 16, v232
	v_and_b32_e32 v23, 0xffff0000, v232
	v_lshlrev_b32_e32 v16, 16, v233
	v_and_b32_e32 v17, 0xffff0000, v233
	v_lshlrev_b32_e32 v24, 16, v234
	v_and_b32_e32 v25, 0xffff0000, v234
	v_lshlrev_b32_e32 v18, 16, v235
	v_and_b32_e32 v19, 0xffff0000, v235
	v_pk_mul_f32 v[14:15], v[14:15], v[16:17]
	v_pk_mul_f32 v[12:13], v[12:13], v[22:23]
	v_pk_mul_f32 v[16:17], v[10:11], v[18:19]
	v_pk_mul_f32 v[10:11], v[8:9], v[24:25]
	v_cvt_pk_bf16_f32 v8, v12, v13
	v_cvt_pk_bf16_f32 v9, v14, v15
	v_cvt_pk_bf16_f32 v10, v10, v11
	v_cvt_pk_bf16_f32 v11, v16, v17
	global_store_dwordx4 v[20:21], v[8:11], off
	s_nop 1
	s_waitcnt vmcnt(15)
	v_lshlrev_b32_e32 v12, 16, v236
	v_and_b32_e32 v13, 0xffff0000, v236
	v_lshlrev_b32_e32 v8, 16, v237
	v_and_b32_e32 v9, 0xffff0000, v237
	v_lshlrev_b32_e32 v14, 16, v238
	v_and_b32_e32 v15, 0xffff0000, v238
	v_lshlrev_b32_e32 v10, 16, v239
	v_and_b32_e32 v11, 0xffff0000, v239
	v_pk_mul_f32 v[6:7], v[6:7], v[8:9]
	v_pk_mul_f32 v[4:5], v[4:5], v[12:13]
	v_pk_mul_f32 v[8:9], v[2:3], v[10:11]
	v_pk_mul_f32 v[2:3], v[0:1], v[14:15]
	v_cvt_pk_bf16_f32 v0, v4, v5
	v_cvt_pk_bf16_f32 v1, v6, v7
	v_cvt_pk_bf16_f32 v2, v2, v3
	v_cvt_pk_bf16_f32 v3, v8, v9
	global_store_dwordx4 v[20:21], v[0:3], off offset:256
	s_cbranch_vccnz .LBB0_446
	s_andn2_b64 vcc, exec, s[8:9]
	s_cbranch_vccnz .LBB0_445
	s_barrier
	s_branch .LBB0_445

; __device__ __forceinline__ void st_bf8(bf16* p, f32x4 a, f32x4 b) { u32x4 w; w.x = pk2(a[0], a[1]); w.y = pk2(a[2], a[3]); w.z = pk2(b[0], b[1]); w.w = pk2(b[2], b[3]); *(u32x4*)p = w; }
; __device__ __forceinline__ void ld_bf8(const bf16* p, f32x4& a, f32x4& b) { const u32x4 w = *(const u32x4*)p; a = (f32x4){bflo(w.x), bfhi(w.x), bflo(w.y), bfhi(w.y)}; b = (f32x4){bflo(w.z), bfhi(w.z), bflo(w.w), bfhi(w.w)}; }
;     __device__ __forceinline__ void operator()(AccRef acc, const pg8::Unit& u, int wr, int wc, int fr, int fq) const {
;         const int c0 = u.pn * 256;
;         EPI_LOOP_P( f32x4 g0, g1, o0, o1; ld_bf8(Gt + rw * 1024 + c0 + cl, g0, g1); ld_bf8(MG + rw * 1024 + c0 + cl, o0, o1); st_bf8(MG + rw * 1024 + c0 + cl, o0 + g0 * v0, o1 + g1 * v1); )
.LBB0_493:
	v_lshl_add_u32 v140, s47, 8, v142
	s_lshl_b32 s20, s48, 8
	v_ashrrev_i32_e32 v141, 31, v140
	s_ashr_i32 s21, s20, 31
	v_lshlrev_b64 v[150:151], 11, v[140:141]
	v_lshl_add_u64 v[146:147], s[12:13], 0, v[150:151]
	s_lshl_b64 s[20:21], s[20:21], 1
	v_lshl_add_u64 v[146:147], v[146:147], 0, s[20:21]
	v_lshl_add_u64 v[152:153], v[146:147], 0, v[184:185]
	v_lshlrev_b32_e32 v244, 11, v140
	v_add3_u32 v244, v244, s20, v184
	global_load_dwordx4 v[166:169], v244, s[12:13]
	global_load_dwordx4 v[170:173], v244, s[10:11]
	global_load_dwordx4 v[174:177], v244, s[12:13] offset:256
	global_load_dwordx4 v[178:181], v244, s[10:11] offset:256
	v_add_u32_e32 v244, 0x8000, v244
	global_load_dwordx4 v[190:193], v244, s[12:13]
	global_load_dwordx4 v[196:199], v244, s[10:11]
	global_load_dwordx4 v[200:203], v244, s[12:13] offset:256
	global_load_dwordx4 v[212:215], v244, s[10:11] offset:256
	v_add_u32_e32 v244, 0x8000, v244
	global_load_dwordx4 v[216:219], v244, s[12:13]
	global_load_dwordx4 v[220:223], v244, s[10:11]
	global_load_dwordx4 v[224:227], v244, s[12:13] offset:256
	global_load_dwordx4 v[228:231], v244, s[10:11] offset:256
	s_and_b64 vcc, exec, s[0:1]
	s_waitcnt vmcnt(11)
	v_lshlrev_b32_e32 v154, 16, v166
	v_and_b32_e32 v155, 0xffff0000, v166
	v_lshlrev_b32_e32 v156, 16, v167
	v_and_b32_e32 v157, 0xffff0000, v167
	v_lshl_add_u64 v[146:147], s[10:11], 0, v[150:151]
	v_lshl_add_u64 v[146:147], v[146:147], 0, s[20:21]
	v_lshl_add_u64 v[150:151], v[146:147], 0, v[184:185]
	v_lshlrev_b32_e32 v158, 16, v168
	v_and_b32_e32 v159, 0xffff0000, v168
	v_lshlrev_b32_e32 v160, 16, v169
	v_and_b32_e32 v161, 0xffff0000, v169
	s_nop 1
	s_waitcnt vmcnt(10)
	v_lshlrev_b32_e32 v162, 16, v170
	v_and_b32_e32 v163, 0xffff0000, v170
	v_lshlrev_b32_e32 v146, 16, v171
	v_and_b32_e32 v147, 0xffff0000, v171
	v_lshlrev_b32_e32 v164, 16, v172
	v_and_b32_e32 v165, 0xffff0000, v172
	v_lshlrev_b32_e32 v148, 16, v173
	v_and_b32_e32 v149, 0xffff0000, v173
	v_pk_fma_f32 v[122:123], v[122:123], v[156:157], v[146:147]
	v_pk_fma_f32 v[120:121], v[120:121], v[154:155], v[162:163]
	v_pk_fma_f32 v[126:127], v[126:127], v[160:161], v[148:149]
	v_pk_fma_f32 v[124:125], v[124:125], v[158:159], v[164:165]
	v_cvt_pk_bf16_f32 v120, v120, v121
	v_cvt_pk_bf16_f32 v121, v122, v123
	v_cvt_pk_bf16_f32 v122, v124, v125
	v_cvt_pk_bf16_f32 v123, v126, v127
	global_store_dwordx4 v[150:151], v[120:123], off
	s_nop 1
	s_waitcnt vmcnt(10)
	v_lshlrev_b32_e32 v124, 16, v174
	v_and_b32_e32 v125, 0xffff0000, v174
	v_lshlrev_b32_e32 v126, 16, v175
	v_and_b32_e32 v127, 0xffff0000, v175
	v_lshlrev_b32_e32 v146, 16, v176
	v_and_b32_e32 v147, 0xffff0000, v176
	v_lshlrev_b32_e32 v148, 16, v177
	v_and_b32_e32 v149, 0xffff0000, v177
	s_nop 1
	s_waitcnt vmcnt(9)
	v_lshlrev_b32_e32 v152, 16, v178
	v_and_b32_e32 v153, 0xffff0000, v178
	v_lshlrev_b32_e32 v120, 16, v179
	v_and_b32_e32 v121, 0xffff0000, v179
	v_lshlrev_b32_e32 v154, 16, v180
	v_and_b32_e32 v155, 0xffff0000, v180
	v_lshlrev_b32_e32 v122, 16, v181
	v_and_b32_e32 v123, 0xffff0000, v181
	v_add_u32_e32 v244, 0x8000, v244
	global_load_dwordx4 v[166:169], v244, s[12:13]
	global_load_dwordx4 v[170:173], v244, s[10:11]
	global_load_dwordx4 v[174:177], v244, s[12:13] offset:256
	global_load_dwordx4 v[178:181], v244, s[10:11] offset:256
	v_pk_fma_f32 v[118:119], v[118:119], v[126:127], v[120:121]
	v_pk_fma_f32 v[116:117], v[116:117], v[124:125], v[152:153]
	v_pk_fma_f32 v[120:121], v[114:115], v[148:149], v[122:123]
	v_pk_fma_f32 v[114:115], v[112:113], v[146:147], v[154:155]
	v_cvt_pk_bf16_f32 v112, v116, v117
	v_cvt_pk_bf16_f32 v113, v118, v119
	v_cvt_pk_bf16_f32 v114, v114, v115
	v_cvt_pk_bf16_f32 v115, v120, v121
	global_store_dwordx4 v[150:151], v[112:115], off offset:256
	s_nop 1
	v_or_b32_e32 v112, 16, v140
	v_ashrrev_i32_e32 v113, 31, v112
	v_lshlrev_b64 v[118:119], 11, v[112:113]
	v_lshl_add_u64 v[112:113], s[12:13], 0, v[118:119]
	v_lshl_add_u64 v[112:113], v[112:113], 0, s[20:21]
	v_lshl_add_u64 v[112:113], v[112:113], 0, v[184:185]
	s_nop 1
	s_waitcnt vmcnt(13)
	v_lshlrev_b32_e32 v120, 16, v190
	v_and_b32_e32 v121, 0xffff0000, v190
	v_lshlrev_b32_e32 v122, 16, v191
	v_and_b32_e32 v123, 0xffff0000, v191
	v_lshl_add_u64 v[114:115], s[10:11], 0, v[118:119]
	v_lshl_add_u64 v[114:115], v[114:115], 0, s[20:21]
	v_lshl_add_u64 v[118:119], v[114:115], 0, v[184:185]
	v_lshlrev_b32_e32 v124, 16, v192
	v_and_b32_e32 v125, 0xffff0000, v192
	v_lshlrev_b32_e32 v126, 16, v193
	v_and_b32_e32 v127, 0xffff0000, v193
	s_nop 1
	s_waitcnt vmcnt(12)
	v_lshlrev_b32_e32 v146, 16, v196
	v_and_b32_e32 v147, 0xffff0000, v196
	v_lshlrev_b32_e32 v114, 16, v197
	v_and_b32_e32 v115, 0xffff0000, v197
	v_lshlrev_b32_e32 v148, 16, v198
	v_and_b32_e32 v149, 0xffff0000, v198
	v_lshlrev_b32_e32 v116, 16, v199
	v_and_b32_e32 v117, 0xffff0000, v199
	v_pk_fma_f32 v[110:111], v[110:111], v[122:123], v[114:115]
	v_pk_fma_f32 v[108:109], v[108:109], v[120:121], v[146:147]
	v_pk_fma_f32 v[114:115], v[106:107], v[126:127], v[116:117]
	v_pk_fma_f32 v[106:107], v[104:105], v[124:125], v[148:149]
	v_cvt_pk_bf16_f32 v104, v108, v109
	v_cvt_pk_bf16_f32 v105, v110, v111
	v_cvt_pk_bf16_f32 v106, v106, v107
	v_cvt_pk_bf16_f32 v107, v114, v115
	global_store_dwordx4 v[118:119], v[104:107], off
	s_nop 1
	s_waitcnt vmcnt(12)
	v_lshlrev_b32_e32 v108, 16, v200
	v_and_b32_e32 v109, 0xffff0000, v200
	v_lshlrev_b32_e32 v110, 16, v201
	v_and_b32_e32 v111, 0xffff0000, v201
	v_lshlrev_b32_e32 v112, 16, v202
	v_and_b32_e32 v113, 0xffff0000, v202
	v_lshlrev_b32_e32 v114, 16, v203
	v_and_b32_e32 v115, 0xffff0000, v203
	s_nop 1
	s_waitcnt vmcnt(11)
; __device__ __forceinline__ void st_bf8(bf16* p, f32x4 a, f32x4 b) { u32x4 w; w.x = pk2(a[0], a[1]); w.y = pk2(a[2], a[3]); w.z = pk2(b[0], b[1]); w.w = pk2(b[2], b[3]); *(u32x4*)p = w; }
; __device__ __forceinline__ void ld_bf8(const bf16* p, f32x4& a, f32x4& b) { const u32x4 w = *(const u32x4*)p; a = (f32x4){bflo(w.x), bfhi(w.x), bflo(w.y), bfhi(w.y)}; b = (f32x4){bflo(w.z), bfhi(w.z), bflo(w.w), bfhi(w.w)}; }
;     __device__ __forceinline__ void operator()(AccRef acc, const pg8::Unit& u, int wr, int wc, int fr, int fq) const {
;         const int c0 = u.pn * 256;
;         EPI_LOOP_P( f32x4 g0, g1, o0, o1; ld_bf8(Gt + rw * 1024 + c0 + cl, g0, g1); ld_bf8(MG + rw * 1024 + c0 + cl, o0, o1); st_bf8(MG + rw * 1024 + c0 + cl, o0 + g0 * v0, o1 + g1 * v1); )
	v_lshlrev_b32_e32 v116, 16, v212
	v_and_b32_e32 v117, 0xffff0000, v212
	v_lshlrev_b32_e32 v104, 16, v213
	v_and_b32_e32 v105, 0xffff0000, v213
	v_lshlrev_b32_e32 v120, 16, v214
	v_and_b32_e32 v121, 0xffff0000, v214
	v_lshlrev_b32_e32 v106, 16, v215
	v_and_b32_e32 v107, 0xffff0000, v215
	v_add_u32_e32 v244, 0x28000, v244
	global_load_dwordx4 v[190:193], v244, s[12:13]
	global_load_dwordx4 v[196:199], v244, s[10:11]
	global_load_dwordx4 v[200:203], v244, s[12:13] offset:256
	global_load_dwordx4 v[212:215], v244, s[10:11] offset:256
	v_pk_fma_f32 v[102:103], v[102:103], v[110:111], v[104:105]
	v_pk_fma_f32 v[100:101], v[100:101], v[108:109], v[116:117]
	v_pk_fma_f32 v[104:105], v[98:99], v[114:115], v[106:107]
	v_pk_fma_f32 v[98:99], v[96:97], v[112:113], v[120:121]
	v_cvt_pk_bf16_f32 v96, v100, v101
	v_cvt_pk_bf16_f32 v97, v102, v103
	v_cvt_pk_bf16_f32 v98, v98, v99
	v_cvt_pk_bf16_f32 v99, v104, v105
	global_store_dwordx4 v[118:119], v[96:99], off offset:256
	s_nop 1
	v_or_b32_e32 v96, 32, v140
	v_ashrrev_i32_e32 v97, 31, v96
	v_lshlrev_b64 v[102:103], 11, v[96:97]
	v_lshl_add_u64 v[96:97], s[12:13], 0, v[102:103]
	v_lshl_add_u64 v[96:97], v[96:97], 0, s[20:21]
	v_lshl_add_u64 v[96:97], v[96:97], 0, v[184:185]
	s_nop 1
	s_waitcnt vmcnt(15)
	v_lshlrev_b32_e32 v104, 16, v216
	v_and_b32_e32 v105, 0xffff0000, v216
	v_lshlrev_b32_e32 v106, 16, v217
	v_and_b32_e32 v107, 0xffff0000, v217
	v_lshl_add_u64 v[98:99], s[10:11], 0, v[102:103]
	v_lshl_add_u64 v[98:99], v[98:99], 0, s[20:21]
	v_lshl_add_u64 v[102:103], v[98:99], 0, v[184:185]
	v_lshlrev_b32_e32 v108, 16, v218
	v_and_b32_e32 v109, 0xffff0000, v218
	v_lshlrev_b32_e32 v110, 16, v219
	v_and_b32_e32 v111, 0xffff0000, v219
	s_nop 1
	s_waitcnt vmcnt(14)
	v_lshlrev_b32_e32 v112, 16, v220
	v_and_b32_e32 v113, 0xffff0000, v220
	v_lshlrev_b32_e32 v98, 16, v221
	v_and_b32_e32 v99, 0xffff0000, v221
	v_lshlrev_b32_e32 v114, 16, v222
	v_and_b32_e32 v115, 0xffff0000, v222
	v_lshlrev_b32_e32 v100, 16, v223
	v_and_b32_e32 v101, 0xffff0000, v223
	v_pk_fma_f32 v[94:95], v[94:95], v[106:107], v[98:99]
	v_pk_fma_f32 v[92:93], v[92:93], v[104:105], v[112:113]
	v_pk_fma_f32 v[98:99], v[90:91], v[110:111], v[100:101]
	v_pk_fma_f32 v[90:91], v[88:89], v[108:109], v[114:115]
	v_cvt_pk_bf16_f32 v88, v92, v93
	v_cvt_pk_bf16_f32 v89, v94, v95
	v_cvt_pk_bf16_f32 v90, v90, v91
	v_cvt_pk_bf16_f32 v91, v98, v99
	global_store_dwordx4 v[102:103], v[88:91], off
	s_nop 1
	s_waitcnt vmcnt(14)
	v_lshlrev_b32_e32 v92, 16, v224
	v_and_b32_e32 v93, 0xffff0000, v224
	v_lshlrev_b32_e32 v94, 16, v225
	v_and_b32_e32 v95, 0xffff0000, v225
	v_lshlrev_b32_e32 v96, 16, v226
	v_and_b32_e32 v97, 0xffff0000, v226
	v_lshlrev_b32_e32 v98, 16, v227
	v_and_b32_e32 v99, 0xffff0000, v227
	s_nop 1
	s_waitcnt vmcnt(13)
	v_lshlrev_b32_e32 v100, 16, v228
	v_and_b32_e32 v101, 0xffff0000, v228
	v_lshlrev_b32_e32 v88, 16, v229
	v_and_b32_e32 v89, 0xffff0000, v229
	v_lshlrev_b32_e32 v104, 16, v230
	v_and_b32_e32 v105, 0xffff0000, v230
	v_lshlrev_b32_e32 v90, 16, v231
	v_and_b32_e32 v91, 0xffff0000, v231
	v_add_u32_e32 v244, 0x8000, v244
	global_load_dwordx4 v[216:219], v244, s[12:13]
	global_load_dwordx4 v[220:223], v244, s[10:11]
	global_load_dwordx4 v[224:227], v244, s[12:13] offset:256
	global_load_dwordx4 v[228:231], v244, s[10:11] offset:256
	v_pk_fma_f32 v[86:87], v[86:87], v[94:95], v[88:89]
	v_pk_fma_f32 v[84:85], v[84:85], v[92:93], v[100:101]
	v_pk_fma_f32 v[88:89], v[82:83], v[98:99], v[90:91]
	v_pk_fma_f32 v[82:83], v[80:81], v[96:97], v[104:105]
	v_cvt_pk_bf16_f32 v80, v84, v85
	v_cvt_pk_bf16_f32 v81, v86, v87
	v_cvt_pk_bf16_f32 v82, v82, v83
	v_cvt_pk_bf16_f32 v83, v88, v89
	global_store_dwordx4 v[102:103], v[80:83], off offset:256
	s_nop 1
	v_or_b32_e32 v80, 48, v140
	v_ashrrev_i32_e32 v81, 31, v80
	v_lshlrev_b64 v[86:87], 11, v[80:81]
	v_lshl_add_u64 v[80:81], s[12:13], 0, v[86:87]
	v_lshl_add_u64 v[80:81], v[80:81], 0, s[20:21]
	v_lshl_add_u64 v[80:81], v[80:81], 0, v[184:185]
	s_nop 1
	s_waitcnt vmcnt(16)
	v_lshlrev_b32_e32 v88, 16, v166
	v_and_b32_e32 v89, 0xffff0000, v166
	v_lshlrev_b32_e32 v90, 16, v167
	v_and_b32_e32 v91, 0xffff0000, v167
	v_lshl_add_u64 v[82:83], s[10:11], 0, v[86:87]
	v_lshl_add_u64 v[82:83], v[82:83], 0, s[20:21]
	v_lshl_add_u64 v[86:87], v[82:83], 0, v[184:185]
	v_lshlrev_b32_e32 v92, 16, v168
	v_and_b32_e32 v93, 0xffff0000, v168
	v_lshlrev_b32_e32 v94, 16, v169
	v_and_b32_e32 v95, 0xffff0000, v169
	s_nop 1
	s_waitcnt vmcnt(15)
	v_lshlrev_b32_e32 v96, 16, v170
	v_and_b32_e32 v97, 0xffff0000, v170
	v_lshlrev_b32_e32 v82, 16, v171
	v_and_b32_e32 v83, 0xffff0000, v171
	v_lshlrev_b32_e32 v98, 16, v172
	v_and_b32_e32 v99, 0xffff0000, v172
	v_lshlrev_b32_e32 v84, 16, v173
	v_and_b32_e32 v85, 0xffff0000, v173
	v_pk_fma_f32 v[78:79], v[78:79], v[90:91], v[82:83]
	v_pk_fma_f32 v[76:77], v[76:77], v[88:89], v[96:97]
	v_pk_fma_f32 v[82:83], v[74:75], v[94:95], v[84:85]
	v_pk_fma_f32 v[74:75], v[72:73], v[92:93], v[98:99]
	v_cvt_pk_bf16_f32 v72, v76, v77
	v_cvt_pk_bf16_f32 v73, v78, v79
	v_cvt_pk_bf16_f32 v74, v74, v75
	v_cvt_pk_bf16_f32 v75, v82, v83
	global_store_dwordx4 v[86:87], v[72:75], off
	s_nop 1
	s_waitcnt vmcnt(15)
	v_lshlrev_b32_e32 v76, 16, v174
	v_and_b32_e32 v77, 0xffff0000, v174
	v_lshlrev_b32_e32 v78, 16, v175
	v_and_b32_e32 v79, 0xffff0000, v175
	v_lshlrev_b32_e32 v80, 16, v176
	v_and_b32_e32 v81, 0xffff0000, v176
	v_lshlrev_b32_e32 v82, 16, v177
	v_and_b32_e32 v83, 0xffff0000, v177
	s_nop 1
	s_waitcnt vmcnt(14)
; __device__ __forceinline__ void st_bf8(bf16* p, f32x4 a, f32x4 b) { u32x4 w; w.x = pk2(a[0], a[1]); w.y = pk2(a[2], a[3]); w.z = pk2(b[0], b[1]); w.w = pk2(b[2], b[3]); *(u32x4*)p = w; }
; __device__ __forceinline__ void ld_bf8(const bf16* p, f32x4& a, f32x4& b) { const u32x4 w = *(const u32x4*)p; a = (f32x4){bflo(w.x), bfhi(w.x), bflo(w.y), bfhi(w.y)}; b = (f32x4){bflo(w.z), bfhi(w.z), bflo(w.w), bfhi(w.w)}; }
;     __device__ __forceinline__ void operator()(AccRef acc, const pg8::Unit& u, int wr, int wc, int fr, int fq) const {
;         const int c0 = u.pn * 256;
;         EPI_LOOP_P( f32x4 g0, g1, o0, o1; ld_bf8(Gt + rw * 1024 + c0 + cl, g0, g1); ld_bf8(MG + rw * 1024 + c0 + cl, o0, o1); st_bf8(MG + rw * 1024 + c0 + cl, o0 + g0 * v0, o1 + g1 * v1); )
	v_lshlrev_b32_e32 v84, 16, v178
	v_and_b32_e32 v85, 0xffff0000, v178
	v_lshlrev_b32_e32 v72, 16, v179
	v_and_b32_e32 v73, 0xffff0000, v179
	v_lshlrev_b32_e32 v88, 16, v180
	v_and_b32_e32 v89, 0xffff0000, v180
	v_lshlrev_b32_e32 v74, 16, v181
	v_and_b32_e32 v75, 0xffff0000, v181
	v_add_u32_e32 v244, 0x8000, v244
	global_load_dwordx4 v[166:169], v244, s[12:13]
	global_load_dwordx4 v[170:173], v244, s[10:11]
	global_load_dwordx4 v[174:177], v244, s[12:13] offset:256
	global_load_dwordx4 v[178:181], v244, s[10:11] offset:256
	v_pk_fma_f32 v[70:71], v[70:71], v[78:79], v[72:73]
	v_pk_fma_f32 v[68:69], v[68:69], v[76:77], v[84:85]
	v_pk_fma_f32 v[72:73], v[66:67], v[82:83], v[74:75]
	v_pk_fma_f32 v[66:67], v[64:65], v[80:81], v[88:89]
	v_cvt_pk_bf16_f32 v64, v68, v69
	v_cvt_pk_bf16_f32 v65, v70, v71
	v_cvt_pk_bf16_f32 v66, v66, v67
	v_cvt_pk_bf16_f32 v67, v72, v73
	global_store_dwordx4 v[86:87], v[64:67], off offset:256
	s_nop 1
	v_add_u32_e32 v64, 0x80, v140
	v_ashrrev_i32_e32 v65, 31, v64
	v_lshlrev_b64 v[70:71], 11, v[64:65]
	v_lshl_add_u64 v[64:65], s[12:13], 0, v[70:71]
	v_lshl_add_u64 v[64:65], v[64:65], 0, s[20:21]
	v_lshl_add_u64 v[64:65], v[64:65], 0, v[184:185]
	s_nop 1
	s_waitcnt vmcnt(16)
	v_lshlrev_b32_e32 v72, 16, v190
	v_and_b32_e32 v73, 0xffff0000, v190
	v_lshlrev_b32_e32 v74, 16, v191
	v_and_b32_e32 v75, 0xffff0000, v191
	v_lshl_add_u64 v[66:67], s[10:11], 0, v[70:71]
	v_lshl_add_u64 v[66:67], v[66:67], 0, s[20:21]
	v_lshl_add_u64 v[70:71], v[66:67], 0, v[184:185]
	v_lshlrev_b32_e32 v76, 16, v192
	v_and_b32_e32 v77, 0xffff0000, v192
	v_lshlrev_b32_e32 v78, 16, v193
	v_and_b32_e32 v79, 0xffff0000, v193
	s_nop 1
	s_waitcnt vmcnt(15)
	v_lshlrev_b32_e32 v80, 16, v196
	v_and_b32_e32 v81, 0xffff0000, v196
	v_lshlrev_b32_e32 v66, 16, v197
	v_and_b32_e32 v67, 0xffff0000, v197
	v_lshlrev_b32_e32 v82, 16, v198
	v_and_b32_e32 v83, 0xffff0000, v198
	v_lshlrev_b32_e32 v68, 16, v199
	v_and_b32_e32 v69, 0xffff0000, v199
	v_pk_fma_f32 v[62:63], v[62:63], v[74:75], v[66:67]
	v_pk_fma_f32 v[60:61], v[60:61], v[72:73], v[80:81]
	v_pk_fma_f32 v[66:67], v[58:59], v[78:79], v[68:69]
	v_pk_fma_f32 v[58:59], v[56:57], v[76:77], v[82:83]
	v_cvt_pk_bf16_f32 v56, v60, v61
	v_cvt_pk_bf16_f32 v57, v62, v63
	v_cvt_pk_bf16_f32 v58, v58, v59
	v_cvt_pk_bf16_f32 v59, v66, v67
	global_store_dwordx4 v[70:71], v[56:59], off
	s_nop 1
	s_waitcnt vmcnt(15)
	v_lshlrev_b32_e32 v60, 16, v200
	v_and_b32_e32 v61, 0xffff0000, v200
	v_lshlrev_b32_e32 v62, 16, v201
	v_and_b32_e32 v63, 0xffff0000, v201
	v_lshlrev_b32_e32 v64, 16, v202
	v_and_b32_e32 v65, 0xffff0000, v202
	v_lshlrev_b32_e32 v66, 16, v203
	v_and_b32_e32 v67, 0xffff0000, v203
	s_nop 1
	s_waitcnt vmcnt(14)
	v_lshlrev_b32_e32 v68, 16, v212
	v_and_b32_e32 v69, 0xffff0000, v212
	v_lshlrev_b32_e32 v56, 16, v213
	v_and_b32_e32 v57, 0xffff0000, v213
	v_lshlrev_b32_e32 v72, 16, v214
	v_and_b32_e32 v73, 0xffff0000, v214
	v_lshlrev_b32_e32 v58, 16, v215
	v_and_b32_e32 v59, 0xffff0000, v215
	v_add_u32_e32 v244, 0x8000, v244
	global_load_dwordx4 v[190:193], v244, s[12:13]
	global_load_dwordx4 v[196:199], v244, s[10:11]
	global_load_dwordx4 v[200:203], v244, s[12:13] offset:256
	global_load_dwordx4 v[212:215], v244, s[10:11] offset:256
	v_pk_fma_f32 v[54:55], v[54:55], v[62:63], v[56:57]
	v_pk_fma_f32 v[52:53], v[52:53], v[60:61], v[68:69]
	v_pk_fma_f32 v[56:57], v[50:51], v[66:67], v[58:59]
	v_pk_fma_f32 v[50:51], v[48:49], v[64:65], v[72:73]
	v_cvt_pk_bf16_f32 v48, v52, v53
	v_cvt_pk_bf16_f32 v49, v54, v55
	v_cvt_pk_bf16_f32 v50, v50, v51
	v_cvt_pk_bf16_f32 v51, v56, v57
	global_store_dwordx4 v[70:71], v[48:51], off offset:256
	s_nop 1
	v_add_u32_e32 v48, 0x90, v140
	v_ashrrev_i32_e32 v49, 31, v48
	v_lshlrev_b64 v[54:55], 11, v[48:49]
	v_lshl_add_u64 v[48:49], s[12:13], 0, v[54:55]
	v_lshl_add_u64 v[48:49], v[48:49], 0, s[20:21]
	v_lshl_add_u64 v[48:49], v[48:49], 0, v[184:185]
	s_nop 1
	s_waitcnt vmcnt(16)
	v_lshlrev_b32_e32 v56, 16, v216
	v_and_b32_e32 v57, 0xffff0000, v216
	v_lshlrev_b32_e32 v58, 16, v217
	v_and_b32_e32 v59, 0xffff0000, v217
	v_lshl_add_u64 v[50:51], s[10:11], 0, v[54:55]
	v_lshl_add_u64 v[50:51], v[50:51], 0, s[20:21]
	v_lshl_add_u64 v[54:55], v[50:51], 0, v[184:185]
	v_lshlrev_b32_e32 v60, 16, v218
	v_and_b32_e32 v61, 0xffff0000, v218
	v_lshlrev_b32_e32 v62, 16, v219
	v_and_b32_e32 v63, 0xffff0000, v219
	s_nop 1
	s_waitcnt vmcnt(15)
	v_lshlrev_b32_e32 v64, 16, v220
	v_and_b32_e32 v65, 0xffff0000, v220
	v_lshlrev_b32_e32 v50, 16, v221
	v_and_b32_e32 v51, 0xffff0000, v221
	v_lshlrev_b32_e32 v66, 16, v222
	v_and_b32_e32 v67, 0xffff0000, v222
	v_lshlrev_b32_e32 v52, 16, v223
	v_and_b32_e32 v53, 0xffff0000, v223
	v_pk_fma_f32 v[46:47], v[46:47], v[58:59], v[50:51]
	v_pk_fma_f32 v[44:45], v[44:45], v[56:57], v[64:65]
	v_pk_fma_f32 v[50:51], v[42:43], v[62:63], v[52:53]
	v_pk_fma_f32 v[42:43], v[40:41], v[60:61], v[66:67]
	v_cvt_pk_bf16_f32 v40, v44, v45
	v_cvt_pk_bf16_f32 v41, v46, v47
	v_cvt_pk_bf16_f32 v42, v42, v43
	v_cvt_pk_bf16_f32 v43, v50, v51
	global_store_dwordx4 v[54:55], v[40:43], off
	s_nop 1
	s_waitcnt vmcnt(15)
	v_lshlrev_b32_e32 v44, 16, v224
	v_and_b32_e32 v45, 0xffff0000, v224
	v_lshlrev_b32_e32 v46, 16, v225
	v_and_b32_e32 v47, 0xffff0000, v225
	v_lshlrev_b32_e32 v48, 16, v226
	v_and_b32_e32 v49, 0xffff0000, v226
	v_lshlrev_b32_e32 v50, 16, v227
	v_and_b32_e32 v51, 0xffff0000, v227
	s_nop 1
	s_waitcnt vmcnt(14)
; #define PG8_BAR __builtin_amdgcn_s_barrier()
; __device__ __forceinline__ void st_bf8(bf16* p, f32x4 a, f32x4 b) { u32x4 w; w.x = pk2(a[0], a[1]); w.y = pk2(a[2], a[3]); w.z = pk2(b[0], b[1]); w.w = pk2(b[2], b[3]); *(u32x4*)p = w; }
; __device__ __forceinline__ void ld_bf8(const bf16* p, f32x4& a, f32x4& b) { const u32x4 w = *(const u32x4*)p; a = (f32x4){bflo(w.x), bfhi(w.x), bflo(w.y), bfhi(w.y)}; b = (f32x4){bflo(w.z), bfhi(w.z), bflo(w.w), bfhi(w.w)}; }
; template <class Epi, class Sched, bool ALIGN_EPI = false, bool SP2 = false>
; __device__ __forceinline__ void gemm_phase(PG8_LAS unsigned char* lds, const Gemm g, const Sched& S, const Epi& E, const int tid_in) {
;     ...
;         if (!has_next) break;
; #pragma unroll
;         for (int a = 0; a < 2; ++a)
; #pragma unroll
;             for (int b = 0; b < 2; ++b)
; #pragma unroll
;                 for (int m = 0; m < 4; ++m)
; #pragma unroll
;                     for (int n = 0; n < 2; ++n) acc[a][b][m][n] = (f32x4){0.f, 0.f, 0.f, 0.f};
;         cur = nxt; cA = nA; cB = nB; ++ui;
;         if constexpr (ALIGN_EPI) { if (wr == 1) PG8_BAR; }
;     __device__ __forceinline__ void operator()(AccRef acc, const pg8::Unit& u, int wr, int wc, int fr, int fq) const {
;         const int c0 = u.pn * 256;
;         EPI_LOOP_P( f32x4 g0, g1, o0, o1; ld_bf8(Gt + rw * 1024 + c0 + cl, g0, g1); ld_bf8(MG + rw * 1024 + c0 + cl, o0, o1); st_bf8(MG + rw * 1024 + c0 + cl, o0 + g0 * v0, o1 + g1 * v1); )
	v_lshlrev_b32_e32 v52, 16, v228
	v_and_b32_e32 v53, 0xffff0000, v228
	v_lshlrev_b32_e32 v40, 16, v229
	v_and_b32_e32 v41, 0xffff0000, v229
	v_lshlrev_b32_e32 v56, 16, v230
	v_and_b32_e32 v57, 0xffff0000, v230
	v_lshlrev_b32_e32 v42, 16, v231
	v_and_b32_e32 v43, 0xffff0000, v231
	v_pk_fma_f32 v[38:39], v[38:39], v[46:47], v[40:41]
	v_pk_fma_f32 v[36:37], v[36:37], v[44:45], v[52:53]
	v_pk_fma_f32 v[40:41], v[34:35], v[50:51], v[42:43]
	v_pk_fma_f32 v[34:35], v[32:33], v[48:49], v[56:57]
	v_cvt_pk_bf16_f32 v32, v36, v37
	v_cvt_pk_bf16_f32 v33, v38, v39
	v_cvt_pk_bf16_f32 v34, v34, v35
	v_cvt_pk_bf16_f32 v35, v40, v41
	global_store_dwordx4 v[54:55], v[32:35], off offset:256
	s_nop 1
	v_add_u32_e32 v32, 0xa0, v140
	v_ashrrev_i32_e32 v33, 31, v32
	v_lshlrev_b64 v[38:39], 11, v[32:33]
	v_lshl_add_u64 v[32:33], s[12:13], 0, v[38:39]
	v_lshl_add_u64 v[32:33], v[32:33], 0, s[20:21]
	v_lshl_add_u64 v[32:33], v[32:33], 0, v[184:185]
	s_nop 1
	s_waitcnt vmcnt(12)
	v_lshlrev_b32_e32 v40, 16, v166
	v_and_b32_e32 v41, 0xffff0000, v166
	v_lshlrev_b32_e32 v42, 16, v167
	v_and_b32_e32 v43, 0xffff0000, v167
	v_lshl_add_u64 v[34:35], s[10:11], 0, v[38:39]
	v_lshl_add_u64 v[34:35], v[34:35], 0, s[20:21]
	v_lshl_add_u64 v[38:39], v[34:35], 0, v[184:185]
	v_lshlrev_b32_e32 v44, 16, v168
	v_and_b32_e32 v45, 0xffff0000, v168
	v_lshlrev_b32_e32 v46, 16, v169
	v_and_b32_e32 v47, 0xffff0000, v169
	s_nop 1
	s_waitcnt vmcnt(11)
	v_lshlrev_b32_e32 v48, 16, v170
	v_and_b32_e32 v49, 0xffff0000, v170
	v_lshlrev_b32_e32 v34, 16, v171
	v_and_b32_e32 v35, 0xffff0000, v171
	v_lshlrev_b32_e32 v50, 16, v172
	v_and_b32_e32 v51, 0xffff0000, v172
	v_lshlrev_b32_e32 v36, 16, v173
	v_and_b32_e32 v37, 0xffff0000, v173
	v_pk_fma_f32 v[30:31], v[30:31], v[42:43], v[34:35]
	v_pk_fma_f32 v[28:29], v[28:29], v[40:41], v[48:49]
	v_pk_fma_f32 v[34:35], v[26:27], v[46:47], v[36:37]
	v_pk_fma_f32 v[26:27], v[24:25], v[44:45], v[50:51]
	v_cvt_pk_bf16_f32 v24, v28, v29
	v_cvt_pk_bf16_f32 v25, v30, v31
	v_cvt_pk_bf16_f32 v26, v26, v27
	v_cvt_pk_bf16_f32 v27, v34, v35
	global_store_dwordx4 v[38:39], v[24:27], off
	s_nop 1
	s_waitcnt vmcnt(11)
	v_lshlrev_b32_e32 v28, 16, v174
	v_and_b32_e32 v29, 0xffff0000, v174
	v_lshlrev_b32_e32 v30, 16, v175
	v_and_b32_e32 v31, 0xffff0000, v175
	v_lshlrev_b32_e32 v32, 16, v176
	v_and_b32_e32 v33, 0xffff0000, v176
	v_lshlrev_b32_e32 v34, 16, v177
	v_and_b32_e32 v35, 0xffff0000, v177
	s_nop 1
	s_waitcnt vmcnt(10)
	v_lshlrev_b32_e32 v36, 16, v178
	v_and_b32_e32 v37, 0xffff0000, v178
	v_lshlrev_b32_e32 v24, 16, v179
	v_and_b32_e32 v25, 0xffff0000, v179
	v_lshlrev_b32_e32 v40, 16, v180
	v_and_b32_e32 v41, 0xffff0000, v180
	v_lshlrev_b32_e32 v26, 16, v181
	v_and_b32_e32 v27, 0xffff0000, v181
	v_pk_fma_f32 v[22:23], v[22:23], v[30:31], v[24:25]
	v_pk_fma_f32 v[20:21], v[20:21], v[28:29], v[36:37]
	v_pk_fma_f32 v[24:25], v[18:19], v[34:35], v[26:27]
	v_pk_fma_f32 v[18:19], v[16:17], v[32:33], v[40:41]
	v_cvt_pk_bf16_f32 v16, v20, v21
	v_cvt_pk_bf16_f32 v17, v22, v23
	v_cvt_pk_bf16_f32 v18, v18, v19
	v_cvt_pk_bf16_f32 v19, v24, v25
	global_store_dwordx4 v[38:39], v[16:19], off offset:256
	s_nop 1
	v_add_u32_e32 v16, 0xb0, v140
	v_ashrrev_i32_e32 v17, 31, v16
	v_lshlrev_b64 v[22:23], 11, v[16:17]
	v_lshl_add_u64 v[16:17], s[12:13], 0, v[22:23]
	v_lshl_add_u64 v[16:17], v[16:17], 0, s[20:21]
	v_lshl_add_u64 v[16:17], v[16:17], 0, v[184:185]
	s_nop 1
	s_waitcnt vmcnt(8)
	v_lshlrev_b32_e32 v24, 16, v190
	v_and_b32_e32 v25, 0xffff0000, v190
	v_lshlrev_b32_e32 v26, 16, v191
	v_and_b32_e32 v27, 0xffff0000, v191
	v_lshl_add_u64 v[18:19], s[10:11], 0, v[22:23]
	v_lshl_add_u64 v[18:19], v[18:19], 0, s[20:21]
	v_lshl_add_u64 v[18:19], v[18:19], 0, v[184:185]
	v_lshlrev_b32_e32 v28, 16, v192
	v_and_b32_e32 v29, 0xffff0000, v192
	v_lshlrev_b32_e32 v30, 16, v193
	v_and_b32_e32 v31, 0xffff0000, v193
	s_nop 1
	s_mov_b64 s[20:21], -1
	s_waitcnt vmcnt(7)
	v_lshlrev_b32_e32 v32, 16, v196
	v_and_b32_e32 v33, 0xffff0000, v196
	v_lshlrev_b32_e32 v20, 16, v197
	v_and_b32_e32 v21, 0xffff0000, v197
	v_lshlrev_b32_e32 v34, 16, v198
	v_and_b32_e32 v35, 0xffff0000, v198
	v_lshlrev_b32_e32 v22, 16, v199
	v_and_b32_e32 v23, 0xffff0000, v199
	v_pk_fma_f32 v[14:15], v[14:15], v[26:27], v[20:21]
	v_pk_fma_f32 v[12:13], v[12:13], v[24:25], v[32:33]
	v_pk_fma_f32 v[20:21], v[10:11], v[30:31], v[22:23]
	v_pk_fma_f32 v[10:11], v[8:9], v[28:29], v[34:35]
	v_cvt_pk_bf16_f32 v8, v12, v13
	v_cvt_pk_bf16_f32 v9, v14, v15
	v_cvt_pk_bf16_f32 v10, v10, v11
	v_cvt_pk_bf16_f32 v11, v20, v21
	global_store_dwordx4 v[18:19], v[8:11], off
	s_nop 1
	s_waitcnt vmcnt(7)
	v_lshlrev_b32_e32 v12, 16, v200
	v_and_b32_e32 v13, 0xffff0000, v200
	v_lshlrev_b32_e32 v14, 16, v201
	v_and_b32_e32 v15, 0xffff0000, v201
	v_lshlrev_b32_e32 v16, 16, v202
	v_and_b32_e32 v17, 0xffff0000, v202
	v_lshlrev_b32_e32 v20, 16, v203
	v_and_b32_e32 v21, 0xffff0000, v203
	s_nop 1
	s_waitcnt vmcnt(6)
	v_lshlrev_b32_e32 v22, 16, v212
	v_and_b32_e32 v23, 0xffff0000, v212
	v_lshlrev_b32_e32 v8, 16, v213
	v_and_b32_e32 v9, 0xffff0000, v213
	v_lshlrev_b32_e32 v24, 16, v214
	v_and_b32_e32 v25, 0xffff0000, v214
	v_lshlrev_b32_e32 v10, 16, v215
	v_and_b32_e32 v11, 0xffff0000, v215
	v_pk_fma_f32 v[6:7], v[6:7], v[14:15], v[8:9]
	v_pk_fma_f32 v[4:5], v[4:5], v[12:13], v[22:23]
	v_pk_fma_f32 v[8:9], v[2:3], v[20:21], v[10:11]
	v_pk_fma_f32 v[2:3], v[0:1], v[16:17], v[24:25]
	v_cvt_pk_bf16_f32 v0, v4, v5
	v_cvt_pk_bf16_f32 v1, v6, v7
	v_cvt_pk_bf16_f32 v2, v2, v3
	v_cvt_pk_bf16_f32 v3, v8, v9
	global_store_dwordx4 v[18:19], v[0:3], off offset:256
	s_cbranch_vccnz .LBB0_476
	s_andn2_b64 vcc, exec, s[8:9]
	s_cbranch_vccnz .LBB0_475
	s_barrier
	s_branch .LBB0_475
